# strategy 2 (de-serialisation): A-lat attention item epilogue issues its eight gain-vector loads together and waits once
# baseline (speedup 1.0000x reference)
.LBB0_336:
	s_andn2_b64 vcc, exec, s[22:23]
	s_waitcnt lgkmcnt(0)
	s_barrier
	s_cbranch_vccnz .LBB0_128
	ds_read2st64_b32 v[36:37], v34 offset1:1
	ds_read2st64_b32 v[38:39], v34 offset0:2 offset1:3
	ds_read2st64_b32 v[40:41], v34 offset0:4 offset1:5
	ds_read2st64_b32 v[42:43], v34 offset0:6 offset1:7
	ds_read2st64_b32 v[44:45], v34 offset0:8 offset1:9
	ds_read2st64_b32 v[46:47], v34 offset0:10 offset1:11
	ds_read2st64_b32 v[48:49], v34 offset0:12 offset1:13
	ds_read2st64_b32 v[50:51], v34 offset0:14 offset1:15
	ds_read2st64_b32 v[52:53], v34 offset0:16 offset1:17
	ds_read2st64_b32 v[54:55], v34 offset0:18 offset1:19
	ds_read2st64_b32 v[56:57], v34 offset0:20 offset1:21
	ds_read2st64_b32 v[58:59], v34 offset0:22 offset1:23
	ds_read2st64_b32 v[60:61], v34 offset0:24 offset1:25
	ds_read2st64_b32 v[62:63], v34 offset0:26 offset1:27
	ds_read2st64_b32 v[64:65], v34 offset0:28 offset1:29
	ds_read2st64_b32 v[66:67], v34 offset0:30 offset1:31
	v_sub_f32_e32 v76, 1.0, v35
	v_lshlrev_b64 v[34:35], 11, v[82:83]
	v_lshl_add_u64 v[34:35], s[0:1], 0, v[34:35]
	s_lshl_b32 s20, s12, 1
	v_lshlrev_b32_e32 v70, 2, v93
	v_readlane_b32 s0, v255, 51
	v_lshl_add_u64 v[68:69], v[34:35], 0, s[20:21]
	v_ashrrev_i32_e32 v71, 31, v70
	v_readlane_b32 s1, v255, 52
	v_lshl_add_u64 v[68:69], v[70:71], 1, v[68:69]
	s_waitcnt lgkmcnt(14)
	v_mov_b32_e32 v73, v38
	v_lshl_add_u64 v[34:35], v[70:71], 2, s[0:1]
	v_mov_b32_e32 v71, v32
	v_mov_b32_e32 v32, v31
	v_mov_b32_e32 v38, v37
	v_mov_b32_e32 v70, v30
	v_mov_b32_e32 v72, v36
	v_pk_fma_f32 v[36:37], v[32:33], v[0:1], v[38:39] op_sel_hi:[1,0,1] neg_lo:[0,0,1] neg_hi:[0,0,1]
	v_pk_fma_f32 v[70:71], v[70:71], v[0:1], v[72:73] op_sel_hi:[1,0,1] neg_lo:[0,0,1] neg_hi:[0,0,1]
	v_pk_mul_f32 v[30:31], v[36:37], v[36:37]
	v_mul_f32_e32 v38, v71, v71
	v_pk_fma_f32 v[32:33], v[70:71], v[70:71], v[30:31]
	v_mov_b32_e32 v72, v26
	v_pk_add_f32 v[32:33], v[32:33], v[38:39] op_sel_hi:[1,0]
	v_mov_b32_e32 v73, v28
	v_pk_add_f32 v[38:39], v[32:33], v[30:31] op_sel:[0,1] op_sel_hi:[1,0]
	global_load_dwordx4 v[30:33], v[34:35], off
	global_load_dwordx4 v[208:211], v[34:35], off offset:64
	global_load_dwordx4 v[212:215], v[34:35], off offset:128
	global_load_dwordx4 v[216:219], v[34:35], off offset:192
	global_load_dwordx4 v[220:223], v[34:35], off offset:256
	global_load_dwordx4 v[224:227], v[34:35], off offset:320
	global_load_dwordx4 v[228:231], v[34:35], off offset:384
	global_load_dwordx4 v[232:235], v[34:35], off offset:448
	s_waitcnt lgkmcnt(13)
	v_mov_b32_e32 v74, v40
	s_waitcnt lgkmcnt(12)
	v_mov_b32_e32 v75, v42
	v_pk_fma_f32 v[72:73], v[72:73], v[0:1], v[74:75] op_sel_hi:[1,0,1] neg_lo:[0,0,1] neg_hi:[0,0,1]
	v_mov_b32_e32 v28, v27
	v_mov_b32_e32 v42, v41
	v_pk_fma_f32 v[26:27], v[28:29], v[0:1], v[42:43] op_sel_hi:[1,0,1] neg_lo:[0,0,1] neg_hi:[0,0,1]
	v_pk_fma_f32 v[28:29], v[72:73], v[72:73], v[38:39]
	v_mul_f32_e32 v38, v73, v73
	v_pk_fma_f32 v[28:29], v[26:27], v[26:27], v[28:29]
	s_waitcnt lgkmcnt(11)
	v_mov_b32_e32 v40, v44
	v_pk_add_f32 v[28:29], v[28:29], v[38:39] op_sel_hi:[1,0]
	v_mul_f32_e32 v38, v27, v27
	v_pk_add_f32 v[28:29], v[28:29], v[38:39] op_sel_hi:[1,0]
	v_mov_b32_e32 v38, v22
	v_mov_b32_e32 v39, v24
	s_waitcnt lgkmcnt(10)
	v_mov_b32_e32 v41, v46
	v_pk_fma_f32 v[38:39], v[38:39], v[0:1], v[40:41] op_sel_hi:[1,0,1] neg_lo:[0,0,1] neg_hi:[0,0,1]
	v_mov_b32_e32 v24, v23
	v_mov_b32_e32 v46, v45
	v_pk_fma_f32 v[22:23], v[24:25], v[0:1], v[46:47] op_sel_hi:[1,0,1] neg_lo:[0,0,1] neg_hi:[0,0,1]
	v_pk_fma_f32 v[24:25], v[38:39], v[38:39], v[28:29]
	v_mul_f32_e32 v28, v39, v39
	v_pk_fma_f32 v[24:25], v[22:23], v[22:23], v[24:25]
	s_waitcnt lgkmcnt(9)
	v_mov_b32_e32 v40, v48
	v_pk_add_f32 v[24:25], v[24:25], v[28:29] op_sel_hi:[1,0]
	v_mul_f32_e32 v28, v23, v23
	v_pk_add_f32 v[24:25], v[24:25], v[28:29] op_sel_hi:[1,0]
	v_mov_b32_e32 v28, v18
	v_mov_b32_e32 v29, v20
	s_waitcnt lgkmcnt(8)
	v_mov_b32_e32 v41, v50
	v_pk_fma_f32 v[28:29], v[28:29], v[0:1], v[40:41] op_sel_hi:[1,0,1] neg_lo:[0,0,1] neg_hi:[0,0,1]
	v_mov_b32_e32 v20, v19
	v_mov_b32_e32 v50, v49
	v_pk_fma_f32 v[18:19], v[20:21], v[0:1], v[50:51] op_sel_hi:[1,0,1] neg_lo:[0,0,1] neg_hi:[0,0,1]
	v_pk_fma_f32 v[20:21], v[28:29], v[28:29], v[24:25]
	v_mul_f32_e32 v24, v29, v29
	v_pk_fma_f32 v[20:21], v[18:19], v[18:19], v[20:21]
	s_waitcnt lgkmcnt(7)
	v_mov_b32_e32 v40, v52
	v_pk_add_f32 v[20:21], v[20:21], v[24:25] op_sel_hi:[1,0]
	v_mul_f32_e32 v24, v19, v19
	v_pk_add_f32 v[20:21], v[20:21], v[24:25] op_sel_hi:[1,0]
	v_mov_b32_e32 v24, v14
	v_mov_b32_e32 v25, v16
	s_waitcnt lgkmcnt(6)
	v_mov_b32_e32 v41, v54
	v_pk_fma_f32 v[24:25], v[24:25], v[0:1], v[40:41] op_sel_hi:[1,0,1] neg_lo:[0,0,1] neg_hi:[0,0,1]
	v_mov_b32_e32 v16, v15
	v_mov_b32_e32 v54, v53
	v_pk_fma_f32 v[14:15], v[16:17], v[0:1], v[54:55] op_sel_hi:[1,0,1] neg_lo:[0,0,1] neg_hi:[0,0,1]
	v_pk_fma_f32 v[16:17], v[24:25], v[24:25], v[20:21]
	v_mul_f32_e32 v20, v25, v25
	v_pk_fma_f32 v[16:17], v[14:15], v[14:15], v[16:17]
	s_waitcnt lgkmcnt(5)
	v_mov_b32_e32 v40, v56
	v_pk_add_f32 v[16:17], v[16:17], v[20:21] op_sel_hi:[1,0]
	v_mul_f32_e32 v20, v15, v15
	v_pk_add_f32 v[16:17], v[16:17], v[20:21] op_sel_hi:[1,0]
	v_mov_b32_e32 v20, v10
	v_mov_b32_e32 v21, v12
	s_waitcnt lgkmcnt(4)
	v_mov_b32_e32 v41, v58
	v_pk_fma_f32 v[20:21], v[20:21], v[0:1], v[40:41] op_sel_hi:[1,0,1] neg_lo:[0,0,1] neg_hi:[0,0,1]
	v_mov_b32_e32 v12, v11
	v_mov_b32_e32 v58, v57
	v_pk_fma_f32 v[10:11], v[12:13], v[0:1], v[58:59] op_sel_hi:[1,0,1] neg_lo:[0,0,1] neg_hi:[0,0,1]
	v_pk_fma_f32 v[12:13], v[20:21], v[20:21], v[16:17]
	v_mul_f32_e32 v16, v21, v21
	v_pk_fma_f32 v[12:13], v[10:11], v[10:11], v[12:13]
	s_waitcnt lgkmcnt(3)
	v_mov_b32_e32 v40, v60
	v_pk_add_f32 v[12:13], v[12:13], v[16:17] op_sel_hi:[1,0]
	v_mul_f32_e32 v16, v11, v11
	v_pk_add_f32 v[12:13], v[12:13], v[16:17] op_sel_hi:[1,0]
	v_mov_b32_e32 v16, v6
	v_mov_b32_e32 v17, v8
	s_waitcnt lgkmcnt(2)
	v_mov_b32_e32 v41, v62
	v_pk_fma_f32 v[16:17], v[16:17], v[0:1], v[40:41] op_sel_hi:[1,0,1] neg_lo:[0,0,1] neg_hi:[0,0,1]
	v_mov_b32_e32 v8, v7
	v_mov_b32_e32 v62, v61
	v_pk_fma_f32 v[6:7], v[8:9], v[0:1], v[62:63] op_sel_hi:[1,0,1] neg_lo:[0,0,1] neg_hi:[0,0,1]
	v_pk_fma_f32 v[8:9], v[16:17], v[16:17], v[12:13]
	v_mul_f32_e32 v12, v17, v17
	v_pk_fma_f32 v[8:9], v[6:7], v[6:7], v[8:9]
	s_waitcnt lgkmcnt(1)
	v_mov_b32_e32 v40, v64
	v_pk_add_f32 v[8:9], v[8:9], v[12:13] op_sel_hi:[1,0]
	v_mul_f32_e32 v12, v7, v7
	v_pk_add_f32 v[8:9], v[8:9], v[12:13] op_sel_hi:[1,0]
	v_mov_b32_e32 v12, v2
	v_mov_b32_e32 v13, v4
	s_waitcnt lgkmcnt(0)
	v_mov_b32_e32 v41, v66
	v_pk_fma_f32 v[12:13], v[12:13], v[0:1], v[40:41] op_sel_hi:[1,0,1] neg_lo:[0,0,1] neg_hi:[0,0,1]
	v_mov_b32_e32 v4, v3
	v_mov_b32_e32 v66, v65
	v_pk_fma_f32 v[40:41], v[4:5], v[0:1], v[66:67] op_sel_hi:[1,0,1] neg_lo:[0,0,1] neg_hi:[0,0,1]
	v_pk_fma_f32 v[2:3], v[12:13], v[12:13], v[8:9]
	v_mul_f32_e32 v0, v13, v13
	v_pk_fma_f32 v[2:3], v[40:41], v[40:41], v[2:3]
	s_mov_b32 s0, 0xbdd8000
	v_pk_add_f32 v[2:3], v[2:3], v[0:1] op_sel_hi:[1,0]
	v_mul_f32_e32 v0, v41, v41
	v_pk_add_f32 v[2:3], v[2:3], v[0:1] op_sel_hi:[1,0]
	s_nop 0
	v_mov_b32_e32 v0, v2
	s_nop 1
	v_permlane16_swap_b32_e32 v2, v0
	v_add_f32_e32 v0, v2, v0
	v_mov_b32_e32 v2, v0
	s_nop 1
	v_permlane32_swap_b32_e32 v0, v2
	v_add_f32_e32 v0, v0, v2
	v_fmamk_f32 v0, v0, 0x3c000000, v194
	v_mul_f32_e32 v2, 0x4b800000, v0
	v_cmp_gt_f32_e32 vcc, s15, v0
	s_waitcnt vmcnt(0)
	v_mov_b32_e32 v3, v32
	v_mov_b32_e32 v32, v31
	v_cndmask_b32_e32 v0, v0, v2, vcc
	v_rsq_f32_e32 v0, v0
	v_mov_b32_e32 v2, v30
	v_mul_f32_e32 v4, 0x45800000, v0
	v_cndmask_b32_e32 v0, v0, v4, vcc
	v_mul_f32_e32 v0, v76, v0
	v_pk_mul_f32 v[4:5], v[70:71], v[0:1] op_sel_hi:[1,0]
	v_pk_mul_f32 v[26:27], v[26:27], v[0:1] op_sel_hi:[1,0]
	v_pk_mul_f32 v[2:3], v[2:3], v[4:5]
	v_pk_mul_f32 v[4:5], v[36:37], v[0:1] op_sel_hi:[1,0]
	v_and_b32_sdwa v9, v2, v193 dst_sel:DWORD dst_unused:UNUSED_PAD src0_sel:WORD_1 src1_sel:DWORD
	v_pk_mul_f32 v[4:5], v[32:33], v[4:5]
	v_and_b32_sdwa v8, v3, v193 dst_sel:DWORD dst_unused:UNUSED_PAD src0_sel:WORD_1 src1_sel:DWORD
	v_add3_u32 v2, v2, v9, s87
	v_and_b32_sdwa v9, v4, v193 dst_sel:DWORD dst_unused:UNUSED_PAD src0_sel:WORD_1 src1_sel:DWORD
	v_add3_u32 v3, v3, v8, s87
	v_and_b32_sdwa v8, v5, v193 dst_sel:DWORD dst_unused:UNUSED_PAD src0_sel:WORD_1 src1_sel:DWORD
	v_add3_u32 v4, v4, v9, s87
	v_add3_u32 v5, v5, v8, s87
	v_and_b32_e32 v4, 0xffff0000, v4
	v_and_b32_e32 v5, 0xffff0000, v5
	v_or_b32_sdwa v2, v4, v2 dst_sel:DWORD dst_unused:UNUSED_PAD src0_sel:DWORD src1_sel:WORD_1
	v_add_co_u32_e32 v4, vcc, s0, v68
	v_or_b32_sdwa v3, v5, v3 dst_sel:DWORD dst_unused:UNUSED_PAD src0_sel:DWORD src1_sel:WORD_1
	s_nop 0
	v_addc_co_u32_e32 v5, vcc, 0, v69, vcc
	global_store_dwordx2 v[4:5], v[2:3], off
	s_nop 1
	v_mov_b32_e32 v2, v208
	v_mov_b32_e32 v3, v209
	v_mov_b32_e32 v4, v210
	v_mov_b32_e32 v5, v211
	v_pk_mul_f32 v[30:31], v[72:73], v[0:1] op_sel_hi:[1,0]
	s_mov_b64 s[0:1], 0xbdd8000
	v_lshl_add_u64 v[8:9], v[68:69], 0, s[0:1]
	v_pk_mul_f32 v[22:23], v[22:23], v[0:1] op_sel_hi:[1,0]
	v_pk_mul_f32 v[18:19], v[18:19], v[0:1] op_sel_hi:[1,0]
	v_pk_mul_f32 v[14:15], v[14:15], v[0:1] op_sel_hi:[1,0]
	v_pk_mul_f32 v[10:11], v[10:11], v[0:1] op_sel_hi:[1,0]
	v_pk_mul_f32 v[6:7], v[6:7], v[0:1] op_sel_hi:[1,0]
	v_mov_b32_e32 v33, v4
	v_mov_b32_e32 v4, v3
	v_mov_b32_e32 v32, v2
	v_pk_mul_f32 v[2:3], v[4:5], v[26:27]
	v_pk_mul_f32 v[30:31], v[32:33], v[30:31]
	v_and_b32_sdwa v26, v3, v193 dst_sel:DWORD dst_unused:UNUSED_PAD src0_sel:WORD_1 src1_sel:DWORD
	v_and_b32_sdwa v27, v2, v193 dst_sel:DWORD dst_unused:UNUSED_PAD src0_sel:WORD_1 src1_sel:DWORD
	v_and_b32_sdwa v4, v31, v193 dst_sel:DWORD dst_unused:UNUSED_PAD src0_sel:WORD_1 src1_sel:DWORD
	v_and_b32_sdwa v5, v30, v193 dst_sel:DWORD dst_unused:UNUSED_PAD src0_sel:WORD_1 src1_sel:DWORD
	v_add3_u32 v3, v3, v26, s87
	v_add3_u32 v2, v2, v27, s87
	v_add3_u32 v5, v30, v5, s87
	v_add3_u32 v4, v31, v4, s87
	v_and_b32_e32 v3, 0xffff0000, v3
	v_and_b32_e32 v2, 0xffff0000, v2
	v_or_b32_sdwa v3, v3, v4 dst_sel:DWORD dst_unused:UNUSED_PAD src0_sel:DWORD src1_sel:WORD_1
	v_or_b32_sdwa v2, v2, v5 dst_sel:DWORD dst_unused:UNUSED_PAD src0_sel:DWORD src1_sel:WORD_1
	global_store_dwordx2 v[8:9], v[2:3], off offset:32
	s_nop 1
	v_mov_b32_e32 v2, v212
	v_mov_b32_e32 v3, v213
	v_mov_b32_e32 v4, v214
	v_mov_b32_e32 v5, v215
	v_pk_mul_f32 v[26:27], v[38:39], v[0:1] op_sel_hi:[1,0]
	v_mov_b32_e32 v31, v4
	v_mov_b32_e32 v4, v3
	v_mov_b32_e32 v30, v2
	v_pk_mul_f32 v[4:5], v[22:23], v[4:5]
	v_pk_mul_f32 v[2:3], v[26:27], v[30:31]
	v_and_b32_sdwa v26, v5, v193 dst_sel:DWORD dst_unused:UNUSED_PAD src0_sel:WORD_1 src1_sel:DWORD
	v_and_b32_sdwa v27, v4, v193 dst_sel:DWORD dst_unused:UNUSED_PAD src0_sel:WORD_1 src1_sel:DWORD
	v_and_b32_sdwa v22, v3, v193 dst_sel:DWORD dst_unused:UNUSED_PAD src0_sel:WORD_1 src1_sel:DWORD
	v_and_b32_sdwa v23, v2, v193 dst_sel:DWORD dst_unused:UNUSED_PAD src0_sel:WORD_1 src1_sel:DWORD
	v_add3_u32 v5, v5, v26, s87
	v_add3_u32 v4, v4, v27, s87
	v_add3_u32 v2, v2, v23, s87
	v_add3_u32 v3, v3, v22, s87
	v_and_b32_e32 v5, 0xffff0000, v5
	v_and_b32_e32 v4, 0xffff0000, v4
	v_or_b32_sdwa v3, v5, v3 dst_sel:DWORD dst_unused:UNUSED_PAD src0_sel:DWORD src1_sel:WORD_1
	v_or_b32_sdwa v2, v4, v2 dst_sel:DWORD dst_unused:UNUSED_PAD src0_sel:DWORD src1_sel:WORD_1
	global_store_dwordx2 v[8:9], v[2:3], off offset:64
	s_nop 1
	v_mov_b32_e32 v2, v216
	v_mov_b32_e32 v3, v217
	v_mov_b32_e32 v4, v218
	v_mov_b32_e32 v5, v219
	v_pk_mul_f32 v[22:23], v[28:29], v[0:1] op_sel_hi:[1,0]
	v_mov_b32_e32 v27, v4
	v_mov_b32_e32 v4, v3
	v_mov_b32_e32 v26, v2
	v_pk_mul_f32 v[4:5], v[18:19], v[4:5]
	v_pk_mul_f32 v[2:3], v[22:23], v[26:27]
	v_and_b32_sdwa v22, v5, v193 dst_sel:DWORD dst_unused:UNUSED_PAD src0_sel:WORD_1 src1_sel:DWORD
	v_and_b32_sdwa v23, v4, v193 dst_sel:DWORD dst_unused:UNUSED_PAD src0_sel:WORD_1 src1_sel:DWORD
	v_and_b32_sdwa v18, v3, v193 dst_sel:DWORD dst_unused:UNUSED_PAD src0_sel:WORD_1 src1_sel:DWORD
	v_and_b32_sdwa v19, v2, v193 dst_sel:DWORD dst_unused:UNUSED_PAD src0_sel:WORD_1 src1_sel:DWORD
	v_add3_u32 v5, v5, v22, s87
	v_add3_u32 v4, v4, v23, s87
	v_add3_u32 v2, v2, v19, s87
	v_add3_u32 v3, v3, v18, s87
	v_and_b32_e32 v5, 0xffff0000, v5
	v_and_b32_e32 v4, 0xffff0000, v4
	v_or_b32_sdwa v3, v5, v3 dst_sel:DWORD dst_unused:UNUSED_PAD src0_sel:DWORD src1_sel:WORD_1
	v_or_b32_sdwa v2, v4, v2 dst_sel:DWORD dst_unused:UNUSED_PAD src0_sel:DWORD src1_sel:WORD_1
	global_store_dwordx2 v[8:9], v[2:3], off offset:96
	s_nop 1
	v_mov_b32_e32 v2, v220
	v_mov_b32_e32 v3, v221
	v_mov_b32_e32 v4, v222
	v_mov_b32_e32 v5, v223
	v_pk_mul_f32 v[18:19], v[24:25], v[0:1] op_sel_hi:[1,0]
	v_mov_b32_e32 v23, v4
	v_mov_b32_e32 v4, v3
	v_mov_b32_e32 v22, v2
	v_pk_mul_f32 v[4:5], v[14:15], v[4:5]
	v_pk_mul_f32 v[2:3], v[18:19], v[22:23]
	v_and_b32_sdwa v18, v5, v193 dst_sel:DWORD dst_unused:UNUSED_PAD src0_sel:WORD_1 src1_sel:DWORD
	v_and_b32_sdwa v19, v4, v193 dst_sel:DWORD dst_unused:UNUSED_PAD src0_sel:WORD_1 src1_sel:DWORD
	v_and_b32_sdwa v14, v3, v193 dst_sel:DWORD dst_unused:UNUSED_PAD src0_sel:WORD_1 src1_sel:DWORD
	v_and_b32_sdwa v15, v2, v193 dst_sel:DWORD dst_unused:UNUSED_PAD src0_sel:WORD_1 src1_sel:DWORD
	v_add3_u32 v5, v5, v18, s87
	v_add3_u32 v4, v4, v19, s87
	v_add3_u32 v2, v2, v15, s87
	v_add3_u32 v3, v3, v14, s87
	v_and_b32_e32 v5, 0xffff0000, v5
	v_and_b32_e32 v4, 0xffff0000, v4
	v_or_b32_sdwa v3, v5, v3 dst_sel:DWORD dst_unused:UNUSED_PAD src0_sel:DWORD src1_sel:WORD_1
	v_or_b32_sdwa v2, v4, v2 dst_sel:DWORD dst_unused:UNUSED_PAD src0_sel:DWORD src1_sel:WORD_1
	global_store_dwordx2 v[8:9], v[2:3], off offset:128
	s_nop 1
	v_mov_b32_e32 v2, v224
	v_mov_b32_e32 v3, v225
	v_mov_b32_e32 v4, v226
	v_mov_b32_e32 v5, v227
	v_pk_mul_f32 v[14:15], v[20:21], v[0:1] op_sel_hi:[1,0]
	v_mov_b32_e32 v19, v4
	v_mov_b32_e32 v4, v3
	v_mov_b32_e32 v18, v2
	v_pk_mul_f32 v[4:5], v[10:11], v[4:5]
	v_pk_mul_f32 v[2:3], v[14:15], v[18:19]
	v_and_b32_sdwa v14, v5, v193 dst_sel:DWORD dst_unused:UNUSED_PAD src0_sel:WORD_1 src1_sel:DWORD
	v_and_b32_sdwa v15, v4, v193 dst_sel:DWORD dst_unused:UNUSED_PAD src0_sel:WORD_1 src1_sel:DWORD
	v_and_b32_sdwa v10, v3, v193 dst_sel:DWORD dst_unused:UNUSED_PAD src0_sel:WORD_1 src1_sel:DWORD
	v_and_b32_sdwa v11, v2, v193 dst_sel:DWORD dst_unused:UNUSED_PAD src0_sel:WORD_1 src1_sel:DWORD
	v_add3_u32 v5, v5, v14, s87
	v_add3_u32 v4, v4, v15, s87
	v_add3_u32 v2, v2, v11, s87
	v_add3_u32 v3, v3, v10, s87
	v_and_b32_e32 v5, 0xffff0000, v5
	v_and_b32_e32 v4, 0xffff0000, v4
	v_or_b32_sdwa v3, v5, v3 dst_sel:DWORD dst_unused:UNUSED_PAD src0_sel:DWORD src1_sel:WORD_1
	v_or_b32_sdwa v2, v4, v2 dst_sel:DWORD dst_unused:UNUSED_PAD src0_sel:DWORD src1_sel:WORD_1
	global_store_dwordx2 v[8:9], v[2:3], off offset:160
	s_nop 1
	v_mov_b32_e32 v2, v228
	v_mov_b32_e32 v3, v229
	v_mov_b32_e32 v4, v230
	v_mov_b32_e32 v5, v231
	v_pk_mul_f32 v[10:11], v[16:17], v[0:1] op_sel_hi:[1,0]
	v_mov_b32_e32 v15, v4
	v_mov_b32_e32 v4, v3
	v_mov_b32_e32 v14, v2
	v_pk_mul_f32 v[4:5], v[6:7], v[4:5]
	v_pk_mul_f32 v[2:3], v[10:11], v[14:15]
	v_and_b32_sdwa v10, v5, v193 dst_sel:DWORD dst_unused:UNUSED_PAD src0_sel:WORD_1 src1_sel:DWORD
	v_and_b32_sdwa v11, v4, v193 dst_sel:DWORD dst_unused:UNUSED_PAD src0_sel:WORD_1 src1_sel:DWORD
	v_and_b32_sdwa v6, v3, v193 dst_sel:DWORD dst_unused:UNUSED_PAD src0_sel:WORD_1 src1_sel:DWORD
	v_and_b32_sdwa v7, v2, v193 dst_sel:DWORD dst_unused:UNUSED_PAD src0_sel:WORD_1 src1_sel:DWORD
	v_add3_u32 v5, v5, v10, s87
	v_add3_u32 v4, v4, v11, s87
	v_add3_u32 v2, v2, v7, s87
	v_add3_u32 v3, v3, v6, s87
	v_and_b32_e32 v5, 0xffff0000, v5
	v_and_b32_e32 v4, 0xffff0000, v4
	v_or_b32_sdwa v3, v5, v3 dst_sel:DWORD dst_unused:UNUSED_PAD src0_sel:DWORD src1_sel:WORD_1
	v_or_b32_sdwa v2, v4, v2 dst_sel:DWORD dst_unused:UNUSED_PAD src0_sel:DWORD src1_sel:WORD_1
	global_store_dwordx2 v[8:9], v[2:3], off offset:192
	s_nop 1
	v_mov_b32_e32 v2, v232
	v_mov_b32_e32 v3, v233
	v_mov_b32_e32 v4, v234
	v_mov_b32_e32 v5, v235
	v_pk_mul_f32 v[6:7], v[12:13], v[0:1] op_sel_hi:[1,0]
	v_pk_mul_f32 v[10:11], v[40:41], v[0:1] op_sel_hi:[1,0]
	v_mov_b32_e32 v12, v2
	v_mov_b32_e32 v13, v4
	v_mov_b32_e32 v4, v3
	v_pk_mul_f32 v[2:3], v[6:7], v[12:13]
	v_pk_mul_f32 v[4:5], v[10:11], v[4:5]
	v_and_b32_sdwa v0, v3, v193 dst_sel:DWORD dst_unused:UNUSED_PAD src0_sel:WORD_1 src1_sel:DWORD
	v_and_b32_sdwa v7, v5, v193 dst_sel:DWORD dst_unused:UNUSED_PAD src0_sel:WORD_1 src1_sel:DWORD
	v_and_b32_sdwa v10, v4, v193 dst_sel:DWORD dst_unused:UNUSED_PAD src0_sel:WORD_1 src1_sel:DWORD
	v_and_b32_sdwa v6, v2, v193 dst_sel:DWORD dst_unused:UNUSED_PAD src0_sel:WORD_1 src1_sel:DWORD
	v_add3_u32 v0, v3, v0, s87
	v_add3_u32 v3, v5, v7, s87
	v_add3_u32 v4, v4, v10, s87
	v_add3_u32 v2, v2, v6, s87
	v_and_b32_e32 v3, 0xffff0000, v3
	v_and_b32_e32 v4, 0xffff0000, v4
	v_or_b32_sdwa v3, v3, v0 dst_sel:DWORD dst_unused:UNUSED_PAD src0_sel:DWORD src1_sel:WORD_1
	v_or_b32_sdwa v2, v4, v2 dst_sel:DWORD dst_unused:UNUSED_PAD src0_sel:DWORD src1_sel:WORD_1
	global_store_dwordx2 v[8:9], v[2:3], off offset:224
	s_branch .LBB0_128
